# grid barrier: the first workgroup of an XCD to arrive starts an L2 writeback (not waited), on top of the early-invalidate barrier
# speedup vs baseline: 1.0089x; 1.0089x over previous
; __device__ __forceinline__ unsigned xb_ld(unsigned* p)              { return __hip_atomic_load(p, __ATOMIC_RELAXED, __HIP_MEMORY_SCOPE_AGENT); }
; __device__ __forceinline__ unsigned xb_add(unsigned* p, unsigned v) { return __hip_atomic_fetch_add(p, v, __ATOMIC_RELAXED, __HIP_MEMORY_SCOPE_AGENT); }
; #define XB_SPIN(cond, bar) do { unsigned _sp = 0; while (cond) { __builtin_amdgcn_s_sleep(1); \
;     if ((++_sp & 255u) == 0u) { if (xb_ld(&(bar)[XB_TMO])) break; if (_sp > XB_SPIN_CAP) { atomicAdd(&(bar)[XB_TMO], 1u); break; } } } } while (0)
; __device__ __forceinline__ void xcd_barrier(const XcdBarrier& b) {
;     ...
;         const unsigned old = xb_add(&bar[XB_XSUB(b.x)], 1u);
;         const unsigned gen = old / nloc;
;         if (old + 1u == (gen + 1u) * nloc) {
;             __builtin_amdgcn_fence(__ATOMIC_RELEASE, "agent");
;             asm volatile("s_waitcnt vmcnt(0)" ::: "memory");
;             const unsigned og = xb_add(&bar[XB_TOP], 1u);
;             const unsigned tg = og / nx;
;             if (og + 1u == (tg + 1u) * nx) xb_add(&bar[XB_TOPGEN], 1u);
;             else XB_SPIN(xb_ld(&bar[XB_TOPGEN]) == tg, bar);
;             __builtin_amdgcn_fence(__ATOMIC_ACQUIRE, "agent");
;             xb_add(&bar[XB_XGEN(b.x)], 1u);
;             asm volatile("s_waitcnt vmcnt(0)" ::: "memory");
;         } else {
;             XB_SPIN(xb_ld(&bar[XB_XGEN(b.x)]) == gen, bar);
;             __builtin_amdgcn_fence(__ATOMIC_ACQUIRE, "agent");
;             asm volatile("s_waitcnt vmcnt(0)" ::: "memory");
.LBB0_125:
	s_or_b64 exec, exec, s[8:9]
	v_cvt_f32_u32_e32 v4, v2
	s_waitcnt vmcnt(0)
	v_readfirstlane_b32 s3, v3
	v_sub_u32_e32 v3, 0, v2
	v_rcp_iflag_f32_e32 v4, v4
	v_add_u32_e32 v5, s3, v1
	v_mul_f32_e32 v4, 0x4f7ffffe, v4
	v_cvt_u32_f32_e32 v4, v4
	v_mul_lo_u32 v1, v3, v4
	v_mul_hi_u32 v1, v4, v1
	v_add_u32_e32 v1, v4, v1
	v_mul_hi_u32 v1, v5, v1
	v_mul_lo_u32 v3, v1, v2
	v_sub_u32_e32 v3, v5, v3
	v_add_u32_e32 v4, 1, v1
	v_cmp_ge_u32_e32 vcc, v3, v2
	s_nop 1
	v_cndmask_b32_e32 v1, v1, v4, vcc
	v_sub_u32_e32 v4, v3, v2
	v_cndmask_b32_e32 v3, v3, v4, vcc
	v_add_u32_e32 v4, 1, v1
	v_cmp_ge_u32_e32 vcc, v3, v2
	v_add_u32_e32 v3, 1, v5
	s_nop 0
	v_cndmask_b32_e32 v1, v1, v4, vcc
	v_mul_lo_u32 v4, v2, v1
	v_cmp_ne_u32_e32 vcc, v5, v4
	s_cbranch_vccnz .Lbar_nf0
	buffer_wbl2 sc1
.Lbar_nf0:
	v_add_u32_e32 v2, v4, v2
	v_cmp_ne_u32_e32 vcc, v3, v2
	s_and_saveexec_b64 s[6:7], vcc
	s_xor_b64 s[6:7], exec, s[6:7]
	s_cbranch_execz .LBB0_139
	s_waitcnt lgkmcnt(0)
	buffer_inv sc1
	v_mov_b32_e32 v0, 0x2000
	global_load_dword v0, v0, s[4:5] offset:1024 sc1
	s_add_u32 s12, s4, 0x2400
	s_addc_u32 s13, s5, 0
	s_waitcnt vmcnt(0)
	v_cmp_eq_u32_e32 vcc, v0, v1
	s_and_saveexec_b64 s[8:9], vcc
	s_cbranch_execz .LBB0_138
	s_add_u32 s10, s58, 0x2f80200
	s_addc_u32 s11, s59, 0
	s_mov_b32 s3, 1
	s_mov_b64 s[14:15], 0
	v_mov_b32_e32 v0, 0
	s_branch .LBB0_129

; __device__ __forceinline__ unsigned xb_ld(unsigned* p)              { return __hip_atomic_load(p, __ATOMIC_RELAXED, __HIP_MEMORY_SCOPE_AGENT); }
; __device__ __forceinline__ unsigned xb_add(unsigned* p, unsigned v) { return __hip_atomic_fetch_add(p, v, __ATOMIC_RELAXED, __HIP_MEMORY_SCOPE_AGENT); }
; #define XB_SPIN(cond, bar) do { unsigned _sp = 0; while (cond) { __builtin_amdgcn_s_sleep(1); \
;     if ((++_sp & 255u) == 0u) { if (xb_ld(&(bar)[XB_TMO])) break; if (_sp > XB_SPIN_CAP) { atomicAdd(&(bar)[XB_TMO], 1u); break; } } } } while (0)
; __device__ __forceinline__ void xcd_barrier(const XcdBarrier& b) {
;     ...
;         const unsigned old = xb_add(&bar[XB_XSUB(b.x)], 1u);
;         const unsigned gen = old / nloc;
;         if (old + 1u == (gen + 1u) * nloc) {
;             __builtin_amdgcn_fence(__ATOMIC_RELEASE, "agent");
;             asm volatile("s_waitcnt vmcnt(0)" ::: "memory");
;             const unsigned og = xb_add(&bar[XB_TOP], 1u);
;             const unsigned tg = og / nx;
;             if (og + 1u == (tg + 1u) * nx) xb_add(&bar[XB_TOPGEN], 1u);
;             else XB_SPIN(xb_ld(&bar[XB_TOPGEN]) == tg, bar);
;             __builtin_amdgcn_fence(__ATOMIC_ACQUIRE, "agent");
;             xb_add(&bar[XB_XGEN(b.x)], 1u);
;             asm volatile("s_waitcnt vmcnt(0)" ::: "memory");
;         } else {
;             XB_SPIN(xb_ld(&bar[XB_XGEN(b.x)]) == gen, bar);
;             __builtin_amdgcn_fence(__ATOMIC_ACQUIRE, "agent");
;             asm volatile("s_waitcnt vmcnt(0)" ::: "memory");
.LBB0_1043:
	s_or_b64 exec, exec, s[10:11]
	v_cvt_f32_u32_e32 v4, v2
	s_waitcnt vmcnt(0)
	v_readfirstlane_b32 s3, v3
	v_sub_u32_e32 v3, 0, v2
	v_rcp_iflag_f32_e32 v4, v4
	v_add_u32_e32 v5, s3, v1
	v_mul_f32_e32 v4, 0x4f7ffffe, v4
	v_cvt_u32_f32_e32 v4, v4
	v_mul_lo_u32 v1, v3, v4
	v_mul_hi_u32 v1, v4, v1
	v_add_u32_e32 v1, v4, v1
	v_mul_hi_u32 v1, v5, v1
	v_mul_lo_u32 v3, v1, v2
	v_sub_u32_e32 v3, v5, v3
	v_add_u32_e32 v4, 1, v1
	v_cmp_ge_u32_e32 vcc, v3, v2
	s_nop 1
	v_cndmask_b32_e32 v1, v1, v4, vcc
	v_sub_u32_e32 v4, v3, v2
	v_cndmask_b32_e32 v3, v3, v4, vcc
	v_add_u32_e32 v4, 1, v1
	v_cmp_ge_u32_e32 vcc, v3, v2
	v_add_u32_e32 v3, 1, v5
	s_nop 0
	v_cndmask_b32_e32 v1, v1, v4, vcc
	v_mul_lo_u32 v4, v2, v1
	v_cmp_ne_u32_e32 vcc, v5, v4
	s_cbranch_vccnz .Lbar_nf9
	buffer_wbl2 sc1
.Lbar_nf9:
	v_add_u32_e32 v2, v4, v2
	v_cmp_ne_u32_e32 vcc, v3, v2
	s_and_saveexec_b64 s[6:7], vcc
	s_xor_b64 s[6:7], exec, s[6:7]
	s_cbranch_execz .LBB0_1057
	s_waitcnt lgkmcnt(0)
	buffer_inv sc1
	v_mov_b32_e32 v0, 0x2000
	global_load_dword v0, v0, s[4:5] offset:1024 sc1
	s_add_u32 s14, s4, 0x2400
	s_addc_u32 s15, s5, 0
	s_waitcnt vmcnt(0)
	v_cmp_eq_u32_e32 vcc, v0, v1
	s_and_saveexec_b64 s[10:11], vcc
	s_cbranch_execz .LBB0_1056
	s_add_u32 s12, s58, 0x2f80200
	s_addc_u32 s13, s59, 0
	s_mov_b32 s3, 1
	s_mov_b64 s[16:17], 0
	v_mov_b32_e32 v0, 0
	s_branch .LBB0_1047

; __device__ __forceinline__ unsigned xb_ld(unsigned* p)              { return __hip_atomic_load(p, __ATOMIC_RELAXED, __HIP_MEMORY_SCOPE_AGENT); }
; __device__ __forceinline__ unsigned xb_add(unsigned* p, unsigned v) { return __hip_atomic_fetch_add(p, v, __ATOMIC_RELAXED, __HIP_MEMORY_SCOPE_AGENT); }
; #define XB_SPIN(cond, bar) do { unsigned _sp = 0; while (cond) { __builtin_amdgcn_s_sleep(1); \
;     if ((++_sp & 255u) == 0u) { if (xb_ld(&(bar)[XB_TMO])) break; if (_sp > XB_SPIN_CAP) { atomicAdd(&(bar)[XB_TMO], 1u); break; } } } } while (0)
; __device__ __forceinline__ void xcd_barrier(const XcdBarrier& b) {
;     ...
;         const unsigned old = xb_add(&bar[XB_XSUB(b.x)], 1u);
;         const unsigned gen = old / nloc;
;         if (old + 1u == (gen + 1u) * nloc) {
;             __builtin_amdgcn_fence(__ATOMIC_RELEASE, "agent");
;             asm volatile("s_waitcnt vmcnt(0)" ::: "memory");
;             const unsigned og = xb_add(&bar[XB_TOP], 1u);
;             const unsigned tg = og / nx;
;             if (og + 1u == (tg + 1u) * nx) xb_add(&bar[XB_TOPGEN], 1u);
;             else XB_SPIN(xb_ld(&bar[XB_TOPGEN]) == tg, bar);
;             __builtin_amdgcn_fence(__ATOMIC_ACQUIRE, "agent");
;             xb_add(&bar[XB_XGEN(b.x)], 1u);
;             asm volatile("s_waitcnt vmcnt(0)" ::: "memory");
;         } else {
;             XB_SPIN(xb_ld(&bar[XB_XGEN(b.x)]) == gen, bar);
;             __builtin_amdgcn_fence(__ATOMIC_ACQUIRE, "agent");
;             asm volatile("s_waitcnt vmcnt(0)" ::: "memory");
.LBB0_1188:
	s_or_b64 exec, exec, s[6:7]
	v_cvt_f32_u32_e32 v4, v2
	s_waitcnt vmcnt(0)
	v_readfirstlane_b32 s4, v3
	v_sub_u32_e32 v3, 0, v2
	v_rcp_iflag_f32_e32 v4, v4
	v_add_u32_e32 v5, s4, v1
	v_mul_f32_e32 v4, 0x4f7ffffe, v4
	v_cvt_u32_f32_e32 v4, v4
	v_mul_lo_u32 v1, v3, v4
	v_mul_hi_u32 v1, v4, v1
	v_add_u32_e32 v1, v4, v1
	v_mul_hi_u32 v1, v5, v1
	v_mul_lo_u32 v3, v1, v2
	v_sub_u32_e32 v3, v5, v3
	v_add_u32_e32 v4, 1, v1
	v_cmp_ge_u32_e32 vcc, v3, v2
	s_nop 1
	v_cndmask_b32_e32 v1, v1, v4, vcc
	v_sub_u32_e32 v4, v3, v2
	v_cndmask_b32_e32 v3, v3, v4, vcc
	v_add_u32_e32 v4, 1, v1
	v_cmp_ge_u32_e32 vcc, v3, v2
	v_add_u32_e32 v3, 1, v5
	s_nop 0
	v_cndmask_b32_e32 v1, v1, v4, vcc
	v_mul_lo_u32 v4, v2, v1
	v_cmp_ne_u32_e32 vcc, v5, v4
	s_cbranch_vccnz .Lbar_nf11
	buffer_wbl2 sc1
.Lbar_nf11:
	v_add_u32_e32 v2, v4, v2
	v_cmp_ne_u32_e32 vcc, v3, v2
	s_and_saveexec_b64 s[4:5], vcc
	s_xor_b64 s[4:5], exec, s[4:5]
	s_cbranch_execz .LBB0_1202
	s_waitcnt lgkmcnt(0)
	buffer_inv sc1
	v_mov_b32_e32 v0, 0x2000
	global_load_dword v0, v0, s[2:3] offset:1024 sc1
	s_add_u32 s10, s2, 0x2400
	s_addc_u32 s11, s3, 0
	s_waitcnt vmcnt(0)
	v_cmp_eq_u32_e32 vcc, v0, v1
	s_and_saveexec_b64 s[6:7], vcc
	s_cbranch_execz .LBB0_1201
	s_add_u32 s8, s58, 0x2f80200
	s_addc_u32 s9, s59, 0
	s_mov_b32 s22, 1
	s_mov_b64 s[12:13], 0
	v_mov_b32_e32 v0, 0
	s_branch .LBB0_1192
